# rows phase dt projection: products accumulate directly into the running sums (fma chain), 4 VALU per group instead of 5 (86 of 96 groups)
# baseline (speedup 1.0000x reference)
.LBB0_464:
	s_mov_b32 s2, s89
	s_mov_b32 s3, s90
	s_andn2_b64 vcc, exec, s[2:3]
	s_nop 0
	v_cndmask_b32_e64 v84, 0, 1, s[2:3]
	v_cmp_ne_u32_e64 s[48:49], 1, v84
	s_cbranch_vccnz .LBB0_468
	s_waitcnt vmcnt(10)
	v_mul_f32_e32 v86, v5, v5
	v_mul_f32_e32 v87, v1, v1
	s_waitcnt vmcnt(8)
	v_fma_f32 v84, v4, v4, v86
	v_fma_f32 v85, v0, v0, v87
	v_fma_f32 v84, v6, v6, v84
	v_fma_f32 v85, v2, v2, v85
	v_fma_f32 v84, v7, v7, v84
	v_fma_f32 v85, v3, v3, v85
	v_mul_f32_e32 v88, v15, v15
	v_mul_f32_e32 v89, v11, v11
	v_add_f32_e32 v84, v84, v85
	v_fma_f32 v86, v14, v14, v88
	v_fma_f32 v87, v10, v10, v89
	v_fma_f32 v86, v16, v16, v86
	v_fma_f32 v87, v12, v12, v87
	v_fma_f32 v86, v17, v17, v86
	v_fma_f32 v87, v13, v13, v87
	v_add_f32_e32 v84, v87, v84
	v_add_f32_e32 v84, v86, v84
	s_mov_b32 s2, 0x800000
	s_and_b32 s1, s1, 0xfffff000
	ds_bpermute_b32 v86, v249, v84
	v_add_u32_e32 v98, s1, v101
	ds_read_b128 v[104:107], v98
	s_mov_b32 s60, s83
	s_mov_b32 s62, s87
	s_waitcnt lgkmcnt(1)
	v_add_f32_e32 v84, v84, v86
	s_mov_b32 s63, s88
	s_mov_b32 s61, s84
	ds_bpermute_b32 v86, v248, v84
	s_waitcnt lgkmcnt(0)
	v_add_f32_e32 v84, v84, v86
	s_nop 1
	ds_bpermute_b32 v86, v247, v84
	s_waitcnt lgkmcnt(0)
	v_add_f32_e32 v84, v84, v86
	s_nop 1
	ds_bpermute_b32 v86, v246, v84
	s_waitcnt lgkmcnt(0)
	v_add_f32_e32 v84, v84, v86
	s_nop 1
	ds_bpermute_b32 v86, v245, v84
	s_waitcnt lgkmcnt(0)
	v_add_f32_e32 v84, v84, v86
	s_nop 1
	ds_bpermute_b32 v85, v244, v84
	ds_read_b128 v[86:89], v100 offset:36864
	s_waitcnt lgkmcnt(1)
	v_add_f32_e32 v84, v84, v85
	v_fmamk_f32 v84, v84, 0x3a800000, v218
	v_cmp_gt_f32_e32 vcc, s2, v84
	v_mul_f32_e32 v85, 0x4b800000, v84
	s_nop 0
	v_cndmask_b32_e32 v84, v84, v85, vcc
	v_rsq_f32_e32 v84, v84
	s_nop 0
	v_mul_f32_e32 v85, 0x45800000, v84
	v_cndmask_b32_e32 v84, v84, v85, vcc
	v_add_u32_e32 v85, s1, v102
	ds_read_b128 v[108:111], v85
	v_pk_mul_f32 v[90:91], v[0:1], v[84:85] op_sel_hi:[1,0]
	s_mov_b32 s1, 0xb00000
	s_waitcnt lgkmcnt(1)
	v_pk_mul_f32 v[86:87], v[86:87], v[90:91]
	v_pk_add_f32 v[90:91], v[104:105], 1.0 op_sel_hi:[1,0]
	v_pk_mul_f32 v[118:119], v[4:5], v[84:85] op_sel_hi:[1,0]
	s_waitcnt lgkmcnt(0)
	v_pk_fma_f32 v[112:113], v[90:91], v[86:87], v[108:109]
	v_pk_mul_f32 v[86:87], v[2:3], v[84:85] op_sel_hi:[1,0]
	s_nop 0
	v_pk_mul_f32 v[86:87], v[88:89], v[86:87]
	v_pk_add_f32 v[88:89], v[106:107], 1.0 op_sel_hi:[1,0]
	s_nop 0
	v_pk_fma_f32 v[110:111], v[88:89], v[86:87], v[110:111]
	v_lshl_add_u64 v[86:87], s[62:63], 0, v[70:71]
	v_add_co_u32_e32 v86, vcc, s1, v86
	v_cvt_pk_bf16_f32 v88, v112, v113
	v_cvt_pk_bf16_f32 v89, v110, v111
	v_addc_co_u32_e32 v87, vcc, 0, v87, vcc
	global_store_dwordx2 v[86:87], v[88:89], off
	ds_read_b128 v[88:91], v100
	s_waitcnt lgkmcnt(0)
	v_mul_f32_e32 v107, v89, v113
	v_fmac_f32_e32 v107, v88, v112
	v_fmac_f32_e32 v107, v90, v110
	v_fmac_f32_e32 v107, v91, v111
	ds_read_b128 v[88:91], v100 offset:4096
	s_waitcnt lgkmcnt(0)
	v_mul_f32_e32 v109, v89, v113
	v_fmac_f32_e32 v109, v88, v112
	v_fmac_f32_e32 v109, v90, v110
	v_fmac_f32_e32 v109, v91, v111
	ds_read_b128 v[88:91], v100 offset:8192
	s_waitcnt lgkmcnt(0)
	v_mul_f32_e32 v108, v89, v113
	v_fmac_f32_e32 v108, v88, v112
	v_fmac_f32_e32 v108, v90, v110
	v_fmac_f32_e32 v108, v91, v111
	ds_read_b128 v[88:91], v100 offset:12288
	s_waitcnt lgkmcnt(0)
	v_mul_f32_e32 v106, v89, v113
	v_fmac_f32_e32 v106, v88, v112
	v_fmac_f32_e32 v106, v90, v110
	v_fmac_f32_e32 v106, v91, v111
	ds_read_b128 v[88:91], v100 offset:16384
	s_waitcnt lgkmcnt(0)
	v_mul_f32_e32 v105, v89, v113
	v_fmac_f32_e32 v105, v88, v112
	v_fmac_f32_e32 v105, v90, v110
	v_fmac_f32_e32 v105, v91, v111
	ds_read_b128 v[88:91], v100 offset:20480
	s_waitcnt lgkmcnt(0)
	v_mul_f32_e32 v104, v89, v113
	v_fmac_f32_e32 v104, v88, v112
	v_fmac_f32_e32 v104, v90, v110
	v_fmac_f32_e32 v104, v91, v111
	ds_read_b128 v[88:91], v100 offset:24576
	s_waitcnt lgkmcnt(0)
	v_mul_f32_e32 v103, v89, v113
	v_fmac_f32_e32 v103, v88, v112
	v_fmac_f32_e32 v103, v90, v110
	v_fmac_f32_e32 v103, v91, v111
	ds_read_b128 v[88:91], v100 offset:28672
	s_waitcnt lgkmcnt(0)
	v_mul_f32_e32 v99, v113, v89
	v_fmac_f32_e32 v99, v112, v88
	v_fmac_f32_e32 v99, v110, v90
	v_fmac_f32_e32 v99, v111, v91
	ds_read_b128 v[88:91], v100 offset:37888
	ds_read_b128 v[110:113], v98 offset:1024
	ds_read_b128 v[114:117], v85 offset:1024
	s_waitcnt lgkmcnt(2)
	v_pk_mul_f32 v[88:89], v[118:119], v[88:89]
	s_waitcnt lgkmcnt(1)
	v_pk_add_f32 v[110:111], v[110:111], 1.0 op_sel_hi:[1,0]
	s_waitcnt lgkmcnt(0)
	v_pk_fma_f32 v[88:89], v[88:89], v[110:111], v[114:115]
	v_pk_mul_f32 v[110:111], v[6:7], v[84:85] op_sel_hi:[1,0]
	s_nop 0
	v_pk_mul_f32 v[90:91], v[110:111], v[90:91]
	v_pk_add_f32 v[110:111], v[112:113], 1.0 op_sel_hi:[1,0]
	s_nop 0
	v_pk_fma_f32 v[90:91], v[90:91], v[110:111], v[116:117]
	v_cvt_pk_bf16_f32 v110, v88, v89
	v_cvt_pk_bf16_f32 v111, v90, v91
	global_store_dwordx2 v[86:87], v[110:111], off offset:512
	ds_read_b128 v[110:113], v100 offset:1024
	s_waitcnt lgkmcnt(0)
	v_fmac_f32_e32 v107, v89, v111
	v_fmac_f32_e32 v107, v88, v110
	v_fmac_f32_e32 v107, v90, v112
	v_fmac_f32_e32 v107, v91, v113
	ds_read_b128 v[110:113], v100 offset:5120
	s_waitcnt lgkmcnt(0)
	v_fma_f32 v116, v89, v111, v109
	v_fmac_f32_e32 v116, v88, v110
	v_fmac_f32_e32 v116, v90, v112
	v_fmac_f32_e32 v116, v91, v113
	ds_read_b128 v[110:113], v100 offset:9216
	s_waitcnt lgkmcnt(0)
	v_fma_f32 v117, v89, v111, v108
	v_fmac_f32_e32 v117, v88, v110
	v_fmac_f32_e32 v117, v90, v112
	v_fmac_f32_e32 v117, v91, v113
	ds_read_b128 v[108:111], v100 offset:13312
	s_waitcnt lgkmcnt(0)
	v_fmac_f32_e32 v106, v89, v109
	v_fmac_f32_e32 v106, v88, v108
	v_fmac_f32_e32 v106, v90, v110
	v_fmac_f32_e32 v106, v91, v111
	ds_read_b128 v[108:111], v100 offset:17408
	s_waitcnt lgkmcnt(0)
	v_fma_f32 v118, v89, v109, v105
	v_fmac_f32_e32 v118, v88, v108
	v_fmac_f32_e32 v118, v90, v110
	v_fmac_f32_e32 v118, v91, v111
	ds_read_b128 v[108:111], v100 offset:21504
	s_waitcnt lgkmcnt(0)
	v_fma_f32 v119, v89, v109, v104
	v_fmac_f32_e32 v119, v88, v108
	v_fmac_f32_e32 v119, v90, v110
	v_fmac_f32_e32 v119, v91, v111
	ds_read_b128 v[108:111], v100 offset:25600
	s_waitcnt lgkmcnt(0)
	v_fma_f32 v120, v89, v109, v103
	v_fmac_f32_e32 v120, v88, v108
	v_fmac_f32_e32 v120, v90, v110
	v_fmac_f32_e32 v120, v91, v111
	ds_read_b128 v[108:111], v100 offset:29696
	v_pk_mul_f32 v[104:105], v[10:11], v[84:85] op_sel_hi:[1,0]
	s_waitcnt lgkmcnt(0)
	v_fma_f32 v121, v89, v109, v99
	v_fmac_f32_e32 v121, v88, v108
	v_fmac_f32_e32 v121, v90, v110
	v_fmac_f32_e32 v121, v91, v111
	ds_read_b128 v[88:91], v100 offset:38912
	ds_read_b128 v[108:111], v98 offset:2048
	ds_read_b128 v[112:115], v85 offset:2048
	s_waitcnt lgkmcnt(2)
	v_pk_mul_f32 v[88:89], v[104:105], v[88:89]
	s_waitcnt lgkmcnt(1)
	v_pk_add_f32 v[104:105], v[108:109], 1.0 op_sel_hi:[1,0]
	s_waitcnt lgkmcnt(0)
	v_pk_fma_f32 v[112:113], v[88:89], v[104:105], v[112:113]
	v_pk_mul_f32 v[88:89], v[12:13], v[84:85] op_sel_hi:[1,0]
	s_nop 0
	v_pk_mul_f32 v[88:89], v[88:89], v[90:91]
	v_pk_add_f32 v[90:91], v[110:111], 1.0 op_sel_hi:[1,0]
	s_nop 0
	v_pk_fma_f32 v[110:111], v[88:89], v[90:91], v[114:115]
	v_cvt_pk_bf16_f32 v88, v112, v113
	v_cvt_pk_bf16_f32 v89, v110, v111
	global_store_dwordx2 v[86:87], v[88:89], off offset:1024
	ds_read_b128 v[88:91], v100 offset:2048
	s_waitcnt lgkmcnt(0)
	v_fma_f32 v105, v113, v89, v107
	v_fmac_f32_e32 v105, v112, v88
	v_fmac_f32_e32 v105, v110, v90
	v_fmac_f32_e32 v105, v111, v91
	ds_read_b128 v[88:91], v100 offset:6144
	s_waitcnt lgkmcnt(0)
	v_fma_f32 v122, v113, v89, v116
	v_fmac_f32_e32 v122, v112, v88
	v_fmac_f32_e32 v122, v110, v90
	v_fmac_f32_e32 v122, v111, v91
	ds_read_b128 v[88:91], v100 offset:10240
	s_waitcnt lgkmcnt(0)
	v_fma_f32 v123, v113, v89, v117
	v_fmac_f32_e32 v123, v112, v88
	v_fmac_f32_e32 v123, v110, v90
	v_fmac_f32_e32 v123, v111, v91
	ds_read_b128 v[88:91], v100 offset:14336
	s_waitcnt lgkmcnt(0)
	v_fma_f32 v104, v113, v89, v106
	v_fmac_f32_e32 v104, v112, v88
	v_fmac_f32_e32 v104, v110, v90
	v_fmac_f32_e32 v104, v111, v91
	ds_read_b128 v[88:91], v100 offset:18432
	ds_read_b128 v[106:109], v100 offset:30720
	s_waitcnt lgkmcnt(1)
	v_fma_f32 v103, v113, v89, v118
	v_fmac_f32_e32 v103, v112, v88
	v_fmac_f32_e32 v103, v110, v90
	v_fmac_f32_e32 v103, v111, v91
	ds_read_b128 v[88:91], v100 offset:22528
	s_waitcnt lgkmcnt(0)
	v_fma_f32 v99, v113, v89, v119
	v_fmac_f32_e32 v99, v112, v88
	v_fmac_f32_e32 v99, v110, v90
	v_fmac_f32_e32 v99, v111, v91
	ds_read_b128 v[88:91], v100 offset:26624
	s_waitcnt lgkmcnt(0)
	v_mul_f32_e32 v89, v113, v89
	v_fmac_f32_e32 v89, v112, v88
	v_mul_f32_e32 v88, v113, v107
	v_fmac_f32_e32 v88, v112, v106
	v_fmac_f32_e32 v89, v110, v90
	v_fmac_f32_e32 v88, v110, v108
	v_fmac_f32_e32 v89, v111, v91
	v_fmac_f32_e32 v88, v111, v109
	ds_read_b128 v[106:109], v100 offset:39936
	ds_read_b128 v[110:113], v98 offset:3072
	ds_read_b128 v[114:117], v85 offset:3072
	v_add_f32_e32 v91, v120, v89
	v_add_f32_e32 v90, v121, v88
	v_pk_mul_f32 v[88:89], v[14:15], v[84:85] op_sel_hi:[1,0]
	v_pk_mul_f32 v[84:85], v[16:17], v[84:85] op_sel_hi:[1,0]
	s_waitcnt lgkmcnt(2)
	v_pk_mul_f32 v[88:89], v[88:89], v[106:107]
	s_waitcnt lgkmcnt(1)
	v_pk_add_f32 v[106:107], v[110:111], 1.0 op_sel_hi:[1,0]
	v_pk_mul_f32 v[84:85], v[84:85], v[108:109]
	s_waitcnt lgkmcnt(0)
	v_pk_fma_f32 v[88:89], v[88:89], v[106:107], v[114:115]
	v_pk_add_f32 v[106:107], v[112:113], 1.0 op_sel_hi:[1,0]
	s_nop 0
	v_pk_fma_f32 v[84:85], v[84:85], v[106:107], v[116:117]
	v_cvt_pk_bf16_f32 v106, v88, v89
	v_cvt_pk_bf16_f32 v107, v84, v85
	global_store_dwordx2 v[86:87], v[106:107], off offset:1536
	ds_read_b128 v[106:109], v100 offset:3072
	s_waitcnt lgkmcnt(0)
	v_fma_f32 v86, v89, v107, v105
	v_fmac_f32_e32 v86, v88, v106
	v_fmac_f32_e32 v86, v84, v108
	v_fmac_f32_e32 v86, v85, v109
	ds_read_b128 v[106:109], v100 offset:7168
	s_waitcnt lgkmcnt(0)
	v_fma_f32 v87, v89, v107, v122
	v_fmac_f32_e32 v87, v88, v106
	v_fmac_f32_e32 v87, v84, v108
	v_fmac_f32_e32 v87, v85, v109
	ds_read_b128 v[106:109], v100 offset:11264
	s_waitcnt lgkmcnt(0)
	v_fma_f32 v98, v89, v107, v123
	v_fmac_f32_e32 v98, v88, v106
	v_fmac_f32_e32 v98, v84, v108
	v_fmac_f32_e32 v98, v85, v109
	ds_read_b128 v[106:109], v100 offset:15360
	s_waitcnt lgkmcnt(0)
	v_mul_f32_e32 v105, v89, v107
	v_fmac_f32_e32 v105, v88, v106
	v_fmac_f32_e32 v105, v84, v108
	v_fmac_f32_e32 v105, v85, v109
	v_add_f32_e32 v108, v104, v105
	ds_read_b128 v[104:107], v100 offset:19456
	s_waitcnt lgkmcnt(0)
	v_fmac_f32_e32 v103, v89, v105
	v_fmac_f32_e32 v103, v88, v104
	v_fmac_f32_e32 v103, v84, v106
	v_fmac_f32_e32 v103, v85, v107
	ds_read_b128 v[104:107], v100 offset:23552
	s_waitcnt lgkmcnt(0)
	v_fmac_f32_e32 v99, v89, v105
	v_fmac_f32_e32 v99, v88, v104
	v_fmac_f32_e32 v99, v84, v106
	v_fmac_f32_e32 v99, v85, v107
	ds_read_b128 v[104:107], v100 offset:27648
	s_waitcnt lgkmcnt(0)
	v_fmac_f32_e32 v91, v89, v105
	v_fmac_f32_e32 v91, v88, v104
	v_fmac_f32_e32 v91, v84, v106
	v_fmac_f32_e32 v91, v85, v107
	ds_read_b128 v[104:107], v100 offset:31744
	s_waitcnt lgkmcnt(0)
	v_mul_f32_e32 v89, v89, v105
	v_fmac_f32_e32 v89, v88, v104
	v_fmac_f32_e32 v89, v84, v106
	v_fmac_f32_e32 v89, v85, v107
	v_cndmask_b32_e64 v85, v103, v86, s[40:41]
	v_cndmask_b32_e64 v86, v86, v103, s[40:41]
	ds_bpermute_b32 v86, v249, v86
	v_cndmask_b32_e64 v88, v98, v91, s[40:41]
	ds_bpermute_b32 v88, v249, v88
	v_add_f32_e32 v84, v90, v89
	s_waitcnt lgkmcnt(1)
	v_add_f32_e32 v85, v85, v86
	v_cndmask_b32_e64 v86, v99, v87, s[40:41]
	v_cndmask_b32_e64 v87, v87, v99, s[40:41]
	ds_bpermute_b32 v87, v249, v87
	s_waitcnt lgkmcnt(0)
	v_add_f32_e32 v86, v86, v87
	v_cndmask_b32_e64 v87, v91, v98, s[40:41]
	v_add_f32_e32 v87, v87, v88
	v_cndmask_b32_e64 v88, v84, v108, s[40:41]
	v_cndmask_b32_e64 v84, v108, v84, s[40:41]
	ds_bpermute_b32 v84, v249, v84
	s_waitcnt lgkmcnt(0)
	v_add_f32_e32 v84, v88, v84
	v_cndmask_b32_e64 v88, v87, v85, s[42:43]
	v_cndmask_b32_e64 v85, v85, v87, s[42:43]
	v_cndmask_b32_e64 v87, v84, v86, s[42:43]
	v_cndmask_b32_e64 v84, v86, v84, s[42:43]
	ds_bpermute_b32 v85, v248, v85
	ds_bpermute_b32 v84, v248, v84
	s_waitcnt lgkmcnt(1)
	v_add_f32_e32 v85, v88, v85
	s_waitcnt lgkmcnt(0)
	v_add_f32_e32 v84, v87, v84
	v_cndmask_b32_e64 v86, v84, v85, s[44:45]
	v_cndmask_b32_e64 v84, v85, v84, s[44:45]
	ds_bpermute_b32 v84, v247, v84
	s_waitcnt lgkmcnt(0)
	v_add_f32_e32 v84, v86, v84
	ds_bpermute_b32 v85, v246, v84
	s_waitcnt lgkmcnt(0)
	v_add_f32_e32 v84, v84, v85
	ds_bpermute_b32 v85, v245, v84
	s_waitcnt lgkmcnt(0)
	v_add_f32_e32 v84, v84, v85
	ds_bpermute_b32 v85, v244, v84
	s_and_saveexec_b64 s[18:19], s[46:47]
	s_cbranch_execz .LBB0_467
	s_mov_b32 s60, s83
	s_mov_b32 s62, s87
	s_mov_b32 s63, s88
	s_waitcnt lgkmcnt(0)
	v_add_f32_e32 v86, v84, v85
	s_mov_b32 s61, s84
	v_lshl_add_u64 v[84:85], s[62:63], 0, v[68:69]
	global_store_dword v[84:85], v86, off

.LBB0_487:
	s_waitcnt vmcnt(10)
	v_mul_f32_e32 v86, v23, v23
	v_mul_f32_e32 v87, v19, v19
	s_waitcnt vmcnt(8)
	v_fma_f32 v84, v22, v22, v86
	v_fma_f32 v85, v18, v18, v87
	v_fma_f32 v84, v24, v24, v84
	v_fma_f32 v85, v20, v20, v85
	v_fma_f32 v84, v25, v25, v84
	v_fma_f32 v85, v21, v21, v85
	v_mul_f32_e32 v88, v31, v31
	v_mul_f32_e32 v89, v27, v27
	v_add_f32_e32 v84, v84, v85
	v_fma_f32 v86, v30, v30, v88
	v_fma_f32 v87, v26, v26, v89
	v_fma_f32 v86, v32, v32, v86
	v_fma_f32 v87, v28, v28, v87
	v_fma_f32 v86, v33, v33, v86
	v_fma_f32 v87, v29, v29, v87
	v_add_f32_e32 v84, v87, v84
	v_add_f32_e32 v84, v86, v84
	s_mov_b32 s2, 0x800000
	s_and_b32 s1, s1, 0xfffff000
	ds_bpermute_b32 v86, v249, v84
	v_add_u32_e32 v98, s1, v101
	ds_read_b128 v[94:97], v98
	v_add_u32_e32 v93, s1, v102
	ds_read_b128 v[110:113], v93
	s_waitcnt lgkmcnt(2)
	v_add_f32_e32 v84, v84, v86
	s_ashr_i32 s57, s56, 31
	ds_read_b128 v[114:117], v100
	ds_bpermute_b32 v86, v248, v84
	s_waitcnt lgkmcnt(0)
	v_add_f32_e32 v84, v84, v86
	s_nop 1
	ds_bpermute_b32 v86, v247, v84
	s_waitcnt lgkmcnt(0)
	v_add_f32_e32 v84, v84, v86
	s_nop 1
	ds_bpermute_b32 v86, v246, v84
	s_waitcnt lgkmcnt(0)
	v_add_f32_e32 v84, v84, v86
	s_nop 1
	ds_bpermute_b32 v86, v245, v84
	s_waitcnt lgkmcnt(0)
	v_add_f32_e32 v84, v84, v86
	s_nop 1
	ds_bpermute_b32 v85, v244, v84
	ds_read_b128 v[86:89], v100 offset:36864
	s_waitcnt lgkmcnt(1)
	v_add_f32_e32 v84, v84, v85
	v_fmamk_f32 v84, v84, 0x3a800000, v218
	v_cmp_gt_f32_e32 vcc, s2, v84
	v_mul_f32_e32 v85, 0x4b800000, v84
	s_lshl_b64 s[2:3], s[56:57], 11
	v_cndmask_b32_e32 v84, v84, v85, vcc
	v_rsq_f32_e32 v84, v84
	s_nop 0
	v_mul_f32_e32 v85, 0x45800000, v84
	v_cndmask_b32_e32 v92, v84, v85, vcc
	v_pk_mul_f32 v[84:85], v[18:19], v[92:93] op_sel_hi:[1,0]
	v_pk_mul_f32 v[118:119], v[22:23], v[92:93] op_sel_hi:[1,0]
	s_waitcnt lgkmcnt(0)
	v_pk_mul_f32 v[84:85], v[86:87], v[84:85]
	v_pk_add_f32 v[86:87], v[94:95], 1.0 op_sel_hi:[1,0]
	s_nop 0
	v_pk_fma_f32 v[86:87], v[86:87], v[84:85], v[110:111]
	v_pk_mul_f32 v[84:85], v[20:21], v[92:93] op_sel_hi:[1,0]
	v_mul_f32_e32 v109, v115, v87
	v_pk_mul_f32 v[84:85], v[88:89], v[84:85]
	v_pk_add_f32 v[88:89], v[96:97], 1.0 op_sel_hi:[1,0]
	v_fmac_f32_e32 v109, v114, v86
	v_pk_fma_f32 v[84:85], v[88:89], v[84:85], v[112:113]
	ds_read_b128 v[88:91], v100 offset:4096
	v_fmac_f32_e32 v109, v116, v84
	v_fmac_f32_e32 v109, v117, v85
	ds_read_b128 v[94:97], v100 offset:8192
	s_waitcnt lgkmcnt(1)
	v_mul_f32_e32 v122, v89, v87
	v_fmac_f32_e32 v122, v88, v86
	v_fmac_f32_e32 v122, v90, v84
	v_fmac_f32_e32 v122, v91, v85
	ds_read_b128 v[88:91], v100 offset:12288
	s_waitcnt lgkmcnt(1)
	v_mul_f32_e32 v123, v95, v87
	v_fmac_f32_e32 v123, v94, v86
	v_fmac_f32_e32 v123, v96, v84
	v_fmac_f32_e32 v123, v97, v85
	ds_read_b128 v[94:97], v100 offset:16384
	s_waitcnt lgkmcnt(1)
	v_mul_f32_e32 v99, v89, v87
	v_fmac_f32_e32 v99, v88, v86
	v_fmac_f32_e32 v99, v90, v84
	v_fmac_f32_e32 v99, v91, v85
	ds_read_b128 v[88:91], v100 offset:20480
	ds_read_b128 v[110:113], v100 offset:24576
	s_waitcnt lgkmcnt(2)
	v_mul_f32_e32 v95, v95, v87
	v_fmac_f32_e32 v95, v94, v86
	v_fmac_f32_e32 v95, v96, v84
	s_waitcnt lgkmcnt(1)
	v_mul_f32_e32 v89, v89, v87
	v_fmac_f32_e32 v89, v88, v86
	v_fmac_f32_e32 v89, v90, v84
	v_fmac_f32_e32 v95, v97, v85
	v_fmac_f32_e32 v89, v91, v85
	v_add_f32_e32 v96, 0, v95
	v_add_f32_e32 v95, 0, v89
	ds_read_b128 v[88:91], v100 offset:28672
	s_waitcnt lgkmcnt(1)
	v_mul_f32_e32 v94, v111, v87
	v_fmac_f32_e32 v94, v110, v86
	v_fmac_f32_e32 v94, v112, v84
	v_fmac_f32_e32 v94, v113, v85
	s_waitcnt lgkmcnt(0)
	v_mul_f32_e32 v97, v87, v89
	v_fmac_f32_e32 v97, v86, v88
	v_fmac_f32_e32 v97, v84, v90
	v_fmac_f32_e32 v97, v85, v91
	ds_read_b128 v[88:91], v100 offset:37888
	ds_read_b128 v[110:113], v98 offset:1024
	ds_read_b128 v[114:117], v93 offset:1024
	s_waitcnt lgkmcnt(2)
	v_pk_mul_f32 v[88:89], v[118:119], v[88:89]
	ds_read_b128 v[118:121], v100 offset:1024
	s_waitcnt lgkmcnt(2)
	v_pk_add_f32 v[110:111], v[110:111], 1.0 op_sel_hi:[1,0]
	v_cvt_pk_bf16_f32 v86, v86, v87
	s_waitcnt lgkmcnt(1)
	v_pk_fma_f32 v[88:89], v[88:89], v[110:111], v[114:115]
	v_pk_mul_f32 v[110:111], v[24:25], v[92:93] op_sel_hi:[1,0]
	s_nop 0
	v_pk_mul_f32 v[90:91], v[110:111], v[90:91]
	v_pk_add_f32 v[110:111], v[112:113], 1.0 op_sel_hi:[1,0]
	s_nop 0
	v_pk_fma_f32 v[90:91], v[90:91], v[110:111], v[116:117]
	ds_read_b128 v[110:113], v100 offset:5120
	s_waitcnt lgkmcnt(1)
	v_fmac_f32_e32 v109, v89, v119
	v_fmac_f32_e32 v109, v88, v118
	v_fmac_f32_e32 v109, v90, v120
	v_fmac_f32_e32 v109, v91, v121
	ds_read_b128 v[114:117], v100 offset:9216
	s_waitcnt lgkmcnt(1)
	v_fma_f32 v126, v89, v111, v122
	v_fmac_f32_e32 v126, v88, v110
	v_fmac_f32_e32 v126, v90, v112
	v_fmac_f32_e32 v126, v91, v113
	ds_read_b128 v[110:113], v100 offset:13312
	s_waitcnt lgkmcnt(1)
	v_fma_f32 v127, v89, v115, v123
	v_fmac_f32_e32 v127, v88, v114
	v_fmac_f32_e32 v127, v90, v116
	v_fmac_f32_e32 v127, v91, v117
	ds_read_b128 v[114:117], v100 offset:17408
	s_waitcnt lgkmcnt(1)
	v_fmac_f32_e32 v99, v89, v111
	v_fmac_f32_e32 v99, v88, v110
	v_fmac_f32_e32 v99, v90, v112
	v_fmac_f32_e32 v99, v91, v113
	ds_read_b128 v[110:113], v100 offset:21504
	s_waitcnt lgkmcnt(1)
	v_fma_f32 v128, v89, v115, v96
	v_fmac_f32_e32 v128, v88, v114
	v_fmac_f32_e32 v128, v90, v116
	v_fmac_f32_e32 v128, v91, v117
	ds_read_b128 v[114:117], v100 offset:25600
	s_waitcnt lgkmcnt(1)
	v_fma_f32 v129, v89, v111, v95
	v_fmac_f32_e32 v129, v88, v110
	v_fmac_f32_e32 v129, v90, v112
	v_fmac_f32_e32 v129, v91, v113
	ds_read_b128 v[110:113], v100 offset:29696
	s_waitcnt lgkmcnt(1)
	v_fma_f32 v130, v89, v115, v94
	v_fmac_f32_e32 v130, v88, v114
	v_fmac_f32_e32 v130, v90, v116
	v_fmac_f32_e32 v130, v91, v117
	s_waitcnt lgkmcnt(0)
	v_fma_f32 v131, v89, v111, v97
	v_fmac_f32_e32 v131, v88, v110
	v_fmac_f32_e32 v131, v90, v112
	v_fmac_f32_e32 v131, v91, v113
	ds_read_b128 v[110:113], v100 offset:38912
	ds_read_b128 v[114:117], v98 offset:2048
	ds_read_b128 v[118:121], v93 offset:2048
	ds_read_b128 v[122:125], v100 offset:2048
	v_pk_mul_f32 v[94:95], v[26:27], v[92:93] op_sel_hi:[1,0]
	s_waitcnt lgkmcnt(2)
	v_pk_add_f32 v[96:97], v[114:115], 1.0 op_sel_hi:[1,0]
	v_pk_mul_f32 v[94:95], v[94:95], v[110:111]
	v_pk_add_f32 v[110:111], v[116:117], 1.0 op_sel_hi:[1,0]
	s_waitcnt lgkmcnt(1)
	v_pk_fma_f32 v[94:95], v[94:95], v[96:97], v[118:119]
	v_pk_mul_f32 v[96:97], v[28:29], v[92:93] op_sel_hi:[1,0]
	s_nop 0
	v_pk_mul_f32 v[96:97], v[96:97], v[112:113]
	s_nop 0
	v_pk_fma_f32 v[96:97], v[96:97], v[110:111], v[120:121]
	ds_read_b128 v[110:113], v100 offset:6144
	s_waitcnt lgkmcnt(1)
	v_fma_f32 v132, v95, v123, v109
	v_fmac_f32_e32 v132, v94, v122
	v_fmac_f32_e32 v132, v96, v124
	v_fmac_f32_e32 v132, v97, v125
	ds_read_b128 v[114:117], v100 offset:10240
	s_waitcnt lgkmcnt(1)
	v_fma_f32 v133, v95, v111, v126
	v_fmac_f32_e32 v133, v94, v110
	v_fmac_f32_e32 v133, v96, v112
	v_fmac_f32_e32 v133, v97, v113
	ds_read_b128 v[110:113], v100 offset:14336
	s_waitcnt lgkmcnt(1)
	v_fma_f32 v134, v95, v115, v127
	v_fmac_f32_e32 v134, v94, v114
	v_fmac_f32_e32 v134, v96, v116
	v_fmac_f32_e32 v134, v97, v117
	ds_read_b128 v[114:117], v100 offset:18432
	ds_read_b128 v[118:121], v100 offset:22528
	s_waitcnt lgkmcnt(2)
	v_mul_f32_e32 v109, v95, v111
	v_fmac_f32_e32 v109, v94, v110
	v_fmac_f32_e32 v109, v96, v112
	v_fmac_f32_e32 v109, v97, v113
	v_add_f32_e32 v113, v99, v109
	s_waitcnt lgkmcnt(1)
	v_fma_f32 v111, v95, v115, v128
	v_fmac_f32_e32 v111, v94, v114
	v_fmac_f32_e32 v111, v96, v116
	v_fmac_f32_e32 v111, v97, v117
	ds_read_b128 v[114:117], v100 offset:26624
	s_waitcnt lgkmcnt(1)
	v_fma_f32 v110, v95, v119, v129
	v_fmac_f32_e32 v110, v94, v118
	v_fmac_f32_e32 v110, v96, v120
	v_fmac_f32_e32 v110, v97, v121
	ds_read_b128 v[118:121], v100 offset:30720
	s_waitcnt lgkmcnt(1)
	v_fma_f32 v109, v95, v115, v130
	v_fmac_f32_e32 v109, v94, v114
	v_fmac_f32_e32 v109, v96, v116
	v_fmac_f32_e32 v109, v97, v117
	s_waitcnt lgkmcnt(0)
	v_fma_f32 v112, v95, v119, v131
	v_fmac_f32_e32 v112, v94, v118
	v_fmac_f32_e32 v112, v96, v120
	v_fmac_f32_e32 v112, v97, v121
	ds_read_b128 v[114:117], v100 offset:39936
	ds_read_b128 v[118:121], v98 offset:3072
	ds_read_b128 v[122:125], v93 offset:3072
	v_pk_mul_f32 v[98:99], v[30:31], v[92:93] op_sel_hi:[1,0]
	v_pk_mul_f32 v[92:93], v[32:33], v[92:93] op_sel_hi:[1,0]
	s_waitcnt lgkmcnt(2)
	v_pk_mul_f32 v[98:99], v[98:99], v[114:115]
	s_waitcnt lgkmcnt(1)
	v_pk_add_f32 v[114:115], v[118:119], 1.0 op_sel_hi:[1,0]
	v_pk_mul_f32 v[92:93], v[92:93], v[116:117]
	s_waitcnt lgkmcnt(0)
	v_pk_fma_f32 v[98:99], v[98:99], v[114:115], v[122:123]
	v_pk_add_f32 v[114:115], v[120:121], 1.0 op_sel_hi:[1,0]
	ds_read_b128 v[126:129], v100 offset:3072
	v_pk_fma_f32 v[92:93], v[92:93], v[114:115], v[124:125]
	ds_read_b128 v[114:117], v100 offset:7168
	s_waitcnt lgkmcnt(1)
	v_fma_f32 v122, v99, v127, v132
	v_fmac_f32_e32 v122, v98, v126
	s_waitcnt lgkmcnt(0)
	v_fma_f32 v123, v99, v115, v133
	v_fmac_f32_e32 v123, v98, v114
	v_fmac_f32_e32 v122, v92, v128
	v_fmac_f32_e32 v123, v92, v116
	v_fmac_f32_e32 v122, v93, v129
	v_fmac_f32_e32 v123, v93, v117
	ds_read_b128 v[118:121], v100 offset:11264
	ds_read_b128 v[114:117], v100 offset:15360
	s_waitcnt lgkmcnt(1)
	v_fma_f32 v124, v99, v119, v134
	v_fmac_f32_e32 v124, v98, v118
	s_waitcnt lgkmcnt(0)
	v_fmac_f32_e32 v113, v99, v115
	v_fmac_f32_e32 v113, v98, v114
	v_fmac_f32_e32 v124, v92, v120
	v_fmac_f32_e32 v113, v92, v116
	v_fmac_f32_e32 v124, v93, v121
	v_fmac_f32_e32 v113, v93, v117
	ds_read_b128 v[118:121], v100 offset:19456
	ds_read_b128 v[114:117], v100 offset:23552
	s_waitcnt lgkmcnt(1)
	v_fmac_f32_e32 v111, v99, v119
	v_fmac_f32_e32 v111, v98, v118
	s_waitcnt lgkmcnt(0)
	v_fmac_f32_e32 v110, v99, v115
	v_fmac_f32_e32 v110, v98, v114
	v_fmac_f32_e32 v111, v92, v120
	v_fmac_f32_e32 v110, v92, v116
	v_fmac_f32_e32 v111, v93, v121
	v_fmac_f32_e32 v110, v93, v117
	ds_read_b128 v[118:121], v100 offset:27648
	ds_read_b128 v[114:117], v100 offset:31744
	s_waitcnt lgkmcnt(1)
	v_fmac_f32_e32 v109, v99, v119
	v_fmac_f32_e32 v109, v98, v118
	s_waitcnt lgkmcnt(0)
	v_fmac_f32_e32 v112, v99, v115
	v_fmac_f32_e32 v112, v98, v114
	v_cndmask_b32_e64 v114, v122, v111, s[40:41]
	ds_bpermute_b32 v114, v249, v114
	v_fmac_f32_e32 v109, v92, v120
	v_fmac_f32_e32 v112, v92, v116
	v_fmac_f32_e32 v109, v93, v121
	v_fmac_f32_e32 v112, v93, v117
	v_cndmask_b32_e64 v111, v111, v122, s[40:41]
	s_waitcnt lgkmcnt(0)
	v_add_f32_e32 v111, v111, v114
	v_cndmask_b32_e64 v114, v110, v123, s[40:41]
	v_cndmask_b32_e64 v110, v123, v110, s[40:41]
	v_cndmask_b32_e64 v115, v124, v109, s[40:41]
	v_cndmask_b32_e64 v116, v113, v112, s[40:41]
	ds_bpermute_b32 v110, v249, v110
	ds_bpermute_b32 v115, v249, v115
	ds_bpermute_b32 v108, v249, v116
	v_cndmask_b32_e64 v109, v109, v124, s[40:41]
	v_cndmask_b32_e64 v112, v112, v113, s[40:41]
	s_waitcnt lgkmcnt(2)
	v_add_f32_e32 v110, v114, v110
	s_waitcnt lgkmcnt(1)
	v_add_f32_e32 v109, v109, v115
	s_waitcnt lgkmcnt(0)
	v_add_f32_e32 v108, v112, v108
	v_cndmask_b32_e64 v112, v111, v109, s[42:43]
	v_cndmask_b32_e64 v113, v110, v108, s[42:43]
	ds_bpermute_b32 v112, v248, v112
	ds_bpermute_b32 v107, v248, v113
	v_cndmask_b32_e64 v109, v109, v111, s[42:43]
	v_cndmask_b32_e64 v108, v108, v110, s[42:43]
	s_waitcnt lgkmcnt(1)
	v_add_f32_e32 v109, v109, v112
	s_waitcnt lgkmcnt(0)
	v_add_f32_e32 v107, v108, v107
	v_cndmask_b32_e64 v108, v109, v107, s[44:45]
	ds_bpermute_b32 v106, v247, v108
	v_cndmask_b32_e64 v87, v107, v109, s[44:45]
	s_waitcnt lgkmcnt(0)
	v_add_f32_e32 v108, v87, v106
	ds_bpermute_b32 v105, v246, v108
	v_cvt_pk_bf16_f32 v87, v84, v85
	v_cvt_pk_bf16_f32 v84, v88, v89
	v_lshl_add_u64 v[106:107], v[66:67], 0, s[2:3]
	v_cvt_pk_bf16_f32 v85, v90, v91
	s_waitcnt lgkmcnt(0)
	v_add_f32_e32 v88, v108, v105
	ds_bpermute_b32 v89, v245, v88
	global_store_dwordx2 v[106:107], v[84:85], off offset:512
	global_store_dwordx2 v[106:107], v[86:87], off
	v_cvt_pk_bf16_f32 v86, v94, v95
	v_cvt_pk_bf16_f32 v87, v96, v97
	s_waitcnt lgkmcnt(0)
	v_add_f32_e32 v84, v88, v89
	ds_bpermute_b32 v85, v244, v84
	global_store_dwordx2 v[106:107], v[86:87], off offset:1024
	v_cvt_pk_bf16_f32 v86, v98, v99
	v_cvt_pk_bf16_f32 v87, v92, v93
	global_store_dwordx2 v[106:107], v[86:87], off offset:1536
	s_and_saveexec_b64 s[18:19], s[46:47]
	s_cbranch_execz .LBB0_489
	s_lshl_b64 s[2:3], s[56:57], 5
	s_waitcnt lgkmcnt(0)
	v_add_f32_e32 v86, v84, v85
	v_lshl_add_u64 v[84:85], v[64:65], 0, s[2:3]
	global_store_dword v[84:85], v86, off

.LBB0_505:
	s_waitcnt vmcnt(6)
	v_mul_f32_e32 v78, v43, v43
	v_mul_f32_e32 v79, v47, v47
	s_waitcnt vmcnt(4)
	v_fma_f32 v76, v42, v42, v78
	v_fma_f32 v77, v46, v46, v79
	v_fma_f32 v76, v44, v44, v76
	v_fma_f32 v77, v48, v48, v77
	v_fma_f32 v76, v45, v45, v76
	v_fma_f32 v77, v49, v49, v77
	v_mul_f32_e32 v80, v35, v35
	v_mul_f32_e32 v81, v39, v39
	v_add_f32_e32 v76, v76, v77
	v_fma_f32 v78, v34, v34, v80
	v_fma_f32 v79, v38, v38, v81
	v_fma_f32 v78, v36, v36, v78
	v_fma_f32 v79, v40, v40, v79
	v_fma_f32 v78, v37, v37, v78
	v_fma_f32 v79, v41, v41, v79
	v_and_b32_e32 v77, 64, v220
	v_add_f32_e32 v76, v79, v76
	v_add_f32_e32 v76, v78, v76
	v_add_u32_e32 v77, 64, v77
	s_mov_b32 s2, 0x800000
	s_and_b32 s1, s1, 0xfffff000
	ds_bpermute_b32 v78, v249, v76
	v_add_u32_e32 v84, s1, v101
	ds_read_b128 v[86:89], v100 offset:36864
	ds_read_b128 v[90:93], v84
	s_ashr_i32 s53, s52, 31
	s_waitcnt lgkmcnt(2)
	v_add_f32_e32 v76, v76, v78
	s_nop 1
	ds_bpermute_b32 v78, v248, v76
	s_waitcnt lgkmcnt(0)
	v_add_f32_e32 v76, v76, v78
	s_nop 1
	ds_bpermute_b32 v78, v247, v76
	s_waitcnt lgkmcnt(0)
	v_add_f32_e32 v76, v76, v78
	s_nop 1
	ds_bpermute_b32 v78, v246, v76
	s_waitcnt lgkmcnt(0)
	v_add_f32_e32 v76, v76, v78
	s_nop 1
	ds_bpermute_b32 v83, v245, v76
	s_waitcnt lgkmcnt(0)
	v_add_f32_e32 v76, v76, v83
	v_xor_b32_e32 v83, 1, v220
	v_cmp_lt_i32_e32 vcc, v83, v77
	s_nop 1
	v_cndmask_b32_e32 v77, v220, v83, vcc
	v_lshlrev_b32_e32 v77, 2, v77
	ds_bpermute_b32 v83, v244, v76
	s_waitcnt lgkmcnt(0)
	v_add_f32_e32 v76, v76, v83
	v_fmamk_f32 v76, v76, 0x3a800000, v218
	v_cmp_gt_f32_e32 vcc, s2, v76
	v_mul_f32_e32 v83, 0x4b800000, v76
	s_lshl_b64 s[2:3], s[52:53], 11
	v_cndmask_b32_e32 v76, v76, v83, vcc
	v_rsq_f32_e32 v76, v76
	s_nop 0
	v_mul_f32_e32 v83, 0x45800000, v76
	v_cndmask_b32_e32 v76, v76, v83, vcc
	v_add_u32_e32 v83, s1, v102
	ds_read_b128 v[94:97], v83
	v_pk_mul_f32 v[46:47], v[46:47], v[76:77] op_sel_hi:[1,0]
	v_pk_mul_f32 v[42:43], v[42:43], v[76:77] op_sel_hi:[1,0]
	v_pk_mul_f32 v[46:47], v[86:87], v[46:47]
	v_pk_add_f32 v[86:87], v[90:91], 1.0 op_sel_hi:[1,0]
	v_pk_mul_f32 v[44:45], v[44:45], v[76:77] op_sel_hi:[1,0]
	s_waitcnt lgkmcnt(0)
	v_pk_fma_f32 v[94:95], v[86:87], v[46:47], v[94:95]
	v_pk_mul_f32 v[46:47], v[48:49], v[76:77] op_sel_hi:[1,0]
	v_pk_add_f32 v[48:49], v[92:93], 1.0 op_sel_hi:[1,0]
	v_pk_mul_f32 v[46:47], v[88:89], v[46:47]
	ds_read_b128 v[86:89], v100
	v_pk_fma_f32 v[92:93], v[48:49], v[46:47], v[96:97]
	v_cvt_pk_bf16_f32 v48, v94, v95
	v_cvt_pk_bf16_f32 v49, v92, v93
	v_lshl_add_u64 v[46:47], v[66:67], 0, s[2:3]
	global_store_dwordx2 v[46:47], v[48:49], off
	s_waitcnt lgkmcnt(0)
	v_mul_f32_e32 v103, v87, v95
	v_fmac_f32_e32 v103, v86, v94
	v_fmac_f32_e32 v103, v88, v92
	v_fmac_f32_e32 v103, v89, v93
	ds_read_b128 v[86:89], v100 offset:4096
	v_pk_mul_f32 v[38:39], v[38:39], v[76:77] op_sel_hi:[1,0]
	v_pk_mul_f32 v[34:35], v[34:35], v[76:77] op_sel_hi:[1,0]
	v_pk_mul_f32 v[36:37], v[36:37], v[76:77] op_sel_hi:[1,0]
	s_waitcnt lgkmcnt(0)
	v_mul_f32_e32 v104, v87, v95
	v_fmac_f32_e32 v104, v86, v94
	v_fmac_f32_e32 v104, v88, v92
	v_fmac_f32_e32 v104, v89, v93
	ds_read_b128 v[86:89], v100 offset:8192
	s_waitcnt lgkmcnt(0)
	v_mul_f32_e32 v105, v87, v95
	v_fmac_f32_e32 v105, v86, v94
	v_fmac_f32_e32 v105, v88, v92
	v_fmac_f32_e32 v105, v89, v93
	ds_read_b128 v[86:89], v100 offset:12288
	s_waitcnt lgkmcnt(0)
	v_mul_f32_e32 v87, v87, v95
	v_fmac_f32_e32 v87, v86, v94
	v_fmac_f32_e32 v87, v88, v92
	v_fmac_f32_e32 v87, v89, v93
	ds_read_b128 v[88:91], v100 offset:16384
	s_waitcnt lgkmcnt(0)
	v_mul_f32_e32 v86, v89, v95
	v_fmac_f32_e32 v86, v88, v94
	v_fmac_f32_e32 v86, v90, v92
	v_fmac_f32_e32 v86, v91, v93
	ds_read_b128 v[88:91], v100 offset:20480
	s_waitcnt lgkmcnt(0)
	v_mul_f32_e32 v85, v89, v95
	v_fmac_f32_e32 v85, v88, v94
	v_fmac_f32_e32 v85, v90, v92
	v_fmac_f32_e32 v85, v91, v93
	ds_read_b128 v[88:91], v100 offset:24576
	s_waitcnt lgkmcnt(0)
	v_mul_f32_e32 v49, v89, v95
	v_fmac_f32_e32 v49, v88, v94
	v_fmac_f32_e32 v49, v90, v92
	v_fmac_f32_e32 v49, v91, v93
	ds_read_b128 v[88:91], v100 offset:28672
	s_waitcnt lgkmcnt(0)
	v_mul_f32_e32 v48, v95, v89
	v_fmac_f32_e32 v48, v94, v88
	v_fmac_f32_e32 v48, v92, v90
	v_fmac_f32_e32 v48, v93, v91
	ds_read_b128 v[88:91], v100 offset:37888
	ds_read_b128 v[92:95], v84 offset:1024
	ds_read_b128 v[96:99], v83 offset:1024
	s_waitcnt lgkmcnt(2)
	v_pk_mul_f32 v[42:43], v[42:43], v[88:89]
	s_waitcnt lgkmcnt(1)
	v_pk_add_f32 v[88:89], v[92:93], 1.0 op_sel_hi:[1,0]
	v_pk_mul_f32 v[44:45], v[44:45], v[90:91]
	s_waitcnt lgkmcnt(0)
	v_pk_fma_f32 v[42:43], v[42:43], v[88:89], v[96:97]
	v_pk_add_f32 v[88:89], v[94:95], 1.0 op_sel_hi:[1,0]
	s_nop 0
	v_pk_fma_f32 v[44:45], v[44:45], v[88:89], v[98:99]
	v_cvt_pk_bf16_f32 v88, v42, v43
	v_cvt_pk_bf16_f32 v89, v44, v45
	global_store_dwordx2 v[46:47], v[88:89], off offset:512
	ds_read_b128 v[88:91], v100 offset:1024
	s_waitcnt lgkmcnt(0)
	v_mul_f32_e32 v89, v43, v89
	v_fmac_f32_e32 v89, v42, v88
	v_fmac_f32_e32 v89, v44, v90
	v_fmac_f32_e32 v89, v45, v91
	ds_read_b128 v[90:93], v100 offset:5120
	v_add_f32_e32 v88, v103, v89
	s_waitcnt lgkmcnt(0)
	v_fma_f32 v89, v43, v91, v104
	v_fmac_f32_e32 v89, v42, v90
	v_fmac_f32_e32 v89, v44, v92
	v_fmac_f32_e32 v89, v45, v93
	ds_read_b128 v[90:93], v100 offset:9216
	s_waitcnt lgkmcnt(0)
	v_fma_f32 v98, v43, v91, v105
	v_fmac_f32_e32 v98, v42, v90
	v_fmac_f32_e32 v98, v44, v92
	v_fmac_f32_e32 v98, v45, v93
	ds_read_b128 v[90:93], v100 offset:13312
	s_waitcnt lgkmcnt(0)
	v_fmac_f32_e32 v87, v43, v91
	v_fmac_f32_e32 v87, v42, v90
	v_fmac_f32_e32 v87, v44, v92
	v_fmac_f32_e32 v87, v45, v93
	ds_read_b128 v[90:93], v100 offset:17408
	s_waitcnt lgkmcnt(0)
	v_fmac_f32_e32 v86, v43, v91
	v_fmac_f32_e32 v86, v42, v90
	v_fmac_f32_e32 v86, v44, v92
	v_fmac_f32_e32 v86, v45, v93
	ds_read_b128 v[90:93], v100 offset:21504
	s_waitcnt lgkmcnt(0)
	v_fmac_f32_e32 v85, v43, v91
	v_fmac_f32_e32 v85, v42, v90
	v_fmac_f32_e32 v85, v44, v92
	v_fmac_f32_e32 v85, v45, v93
	ds_read_b128 v[90:93], v100 offset:25600
	s_waitcnt lgkmcnt(0)
	v_fma_f32 v99, v43, v91, v49
	v_fmac_f32_e32 v99, v42, v90
	v_fmac_f32_e32 v99, v44, v92
	v_fmac_f32_e32 v99, v45, v93
	ds_read_b128 v[90:93], v100 offset:29696
	s_waitcnt lgkmcnt(0)
	v_fma_f32 v103, v43, v91, v48
	v_fmac_f32_e32 v103, v42, v90
	v_fmac_f32_e32 v103, v44, v92
	v_fmac_f32_e32 v103, v45, v93
	ds_read_b128 v[42:45], v100 offset:38912
	ds_read_b128 v[90:93], v84 offset:2048
	ds_read_b128 v[94:97], v83 offset:2048
	s_waitcnt lgkmcnt(2)
	v_pk_mul_f32 v[38:39], v[38:39], v[42:43]
	s_waitcnt lgkmcnt(1)
	v_pk_add_f32 v[42:43], v[90:91], 1.0 op_sel_hi:[1,0]
	s_waitcnt lgkmcnt(0)
	v_pk_fma_f32 v[48:49], v[38:39], v[42:43], v[94:95]
	v_pk_mul_f32 v[38:39], v[40:41], v[76:77] op_sel_hi:[1,0]
	v_pk_add_f32 v[40:41], v[92:93], 1.0 op_sel_hi:[1,0]
	v_pk_mul_f32 v[38:39], v[38:39], v[44:45]
	s_nop 0
	v_pk_fma_f32 v[44:45], v[38:39], v[40:41], v[96:97]
	v_cvt_pk_bf16_f32 v38, v48, v49
	v_cvt_pk_bf16_f32 v39, v44, v45
	global_store_dwordx2 v[46:47], v[38:39], off offset:1024
	ds_read_b128 v[38:41], v100 offset:2048
	s_waitcnt lgkmcnt(0)
	v_fma_f32 v43, v49, v39, v88
	v_fmac_f32_e32 v43, v48, v38
	v_fmac_f32_e32 v43, v44, v40
	v_fmac_f32_e32 v43, v45, v41
	ds_read_b128 v[38:41], v100 offset:6144
	s_waitcnt lgkmcnt(0)
	v_fma_f32 v104, v49, v39, v89
	v_fmac_f32_e32 v104, v48, v38
	v_fmac_f32_e32 v104, v44, v40
	v_fmac_f32_e32 v104, v45, v41
	ds_read_b128 v[38:41], v100 offset:10240
	s_waitcnt lgkmcnt(0)
	v_fmac_f32_e32 v98, v49, v39
	v_fmac_f32_e32 v98, v48, v38
	v_fmac_f32_e32 v98, v44, v40
	v_fmac_f32_e32 v98, v45, v41
	ds_read_b128 v[38:41], v100 offset:14336
	s_waitcnt lgkmcnt(0)
	v_fma_f32 v42, v49, v39, v87
	v_fmac_f32_e32 v42, v48, v38
	v_fmac_f32_e32 v42, v44, v40
	v_fmac_f32_e32 v42, v45, v41
	ds_read_b128 v[38:41], v100 offset:18432
	s_waitcnt lgkmcnt(0)
	v_mul_f32_e32 v39, v49, v39
	v_fmac_f32_e32 v39, v48, v38
	v_fmac_f32_e32 v39, v44, v40
	v_fmac_f32_e32 v39, v45, v41
	v_add_f32_e32 v41, v86, v39
	ds_read_b128 v[86:89], v100 offset:22528
	s_waitcnt lgkmcnt(0)
	v_fma_f32 v40, v49, v87, v85
	v_fmac_f32_e32 v40, v48, v86
	v_fmac_f32_e32 v40, v44, v88
	v_fmac_f32_e32 v40, v45, v89
	ds_read_b128 v[86:89], v100 offset:26624
	s_waitcnt lgkmcnt(0)
	v_fma_f32 v39, v49, v87, v99
	v_fmac_f32_e32 v39, v48, v86
	v_fmac_f32_e32 v39, v44, v88
	v_fmac_f32_e32 v39, v45, v89
	ds_read_b128 v[86:89], v100 offset:30720
	s_waitcnt lgkmcnt(0)
	v_fma_f32 v38, v49, v87, v103
	v_fmac_f32_e32 v38, v48, v86
	v_fmac_f32_e32 v38, v44, v88
	v_fmac_f32_e32 v38, v45, v89
	ds_read_b128 v[86:89], v100 offset:39936
	ds_read_b128 v[90:93], v84 offset:3072
	ds_read_b128 v[94:97], v83 offset:3072
	s_waitcnt lgkmcnt(2)
	v_pk_mul_f32 v[34:35], v[34:35], v[86:87]
	s_waitcnt lgkmcnt(1)
	v_pk_add_f32 v[44:45], v[90:91], 1.0 op_sel_hi:[1,0]
	v_pk_mul_f32 v[36:37], v[36:37], v[88:89]
	s_waitcnt lgkmcnt(0)
	v_pk_fma_f32 v[34:35], v[34:35], v[44:45], v[94:95]
	v_pk_add_f32 v[44:45], v[92:93], 1.0 op_sel_hi:[1,0]
	s_nop 0
	v_pk_fma_f32 v[36:37], v[36:37], v[44:45], v[96:97]
	v_cvt_pk_bf16_f32 v44, v34, v35
	v_cvt_pk_bf16_f32 v45, v36, v37
	global_store_dwordx2 v[46:47], v[44:45], off offset:1536
	ds_read_b128 v[44:47], v100 offset:3072
	s_waitcnt lgkmcnt(0)
	v_fmac_f32_e32 v43, v35, v45
	v_fmac_f32_e32 v43, v34, v44
	v_fmac_f32_e32 v43, v36, v46
	v_fmac_f32_e32 v43, v37, v47
	ds_read_b128 v[44:47], v100 offset:7168
	s_waitcnt lgkmcnt(0)
	v_fma_f32 v48, v35, v45, v104
	v_fmac_f32_e32 v48, v34, v44
	v_fmac_f32_e32 v48, v36, v46
	v_fmac_f32_e32 v48, v37, v47
	ds_read_b128 v[44:47], v100 offset:11264
	s_waitcnt lgkmcnt(0)
	v_fma_f32 v49, v35, v45, v98
	v_fmac_f32_e32 v49, v34, v44
	v_fmac_f32_e32 v49, v36, v46
	v_fmac_f32_e32 v49, v37, v47
	ds_read_b128 v[44:47], v100 offset:15360
	s_waitcnt lgkmcnt(0)
	v_fmac_f32_e32 v42, v35, v45
	v_fmac_f32_e32 v42, v34, v44
	v_fmac_f32_e32 v42, v36, v46
	v_fmac_f32_e32 v42, v37, v47
	ds_read_b128 v[44:47], v100 offset:19456
	s_waitcnt lgkmcnt(0)
	v_fmac_f32_e32 v41, v35, v45
	v_fmac_f32_e32 v41, v34, v44
	v_fmac_f32_e32 v41, v36, v46
	v_fmac_f32_e32 v41, v37, v47
	ds_read_b128 v[44:47], v100 offset:23552
	s_waitcnt lgkmcnt(0)
	v_fmac_f32_e32 v40, v35, v45
	v_fmac_f32_e32 v40, v34, v44
	v_fmac_f32_e32 v40, v36, v46
	v_fmac_f32_e32 v40, v37, v47
	ds_read_b128 v[44:47], v100 offset:27648
	s_waitcnt lgkmcnt(0)
	v_fmac_f32_e32 v39, v35, v45
	v_fmac_f32_e32 v39, v34, v44
	v_fmac_f32_e32 v39, v36, v46
	v_fmac_f32_e32 v39, v37, v47
	ds_read_b128 v[44:47], v100 offset:31744
	s_waitcnt lgkmcnt(0)
	v_mul_f32_e32 v35, v35, v45
	v_fmac_f32_e32 v35, v34, v44
	v_fmac_f32_e32 v35, v36, v46
	v_cndmask_b32_e64 v36, v43, v41, s[40:41]
	v_fmac_f32_e32 v35, v37, v47
	ds_bpermute_b32 v36, v249, v36
	v_cndmask_b32_e64 v37, v48, v40, s[40:41]
	v_add_f32_e32 v34, v38, v35
	ds_bpermute_b32 v37, v249, v37
	v_cndmask_b32_e64 v38, v49, v39, s[40:41]
	ds_bpermute_b32 v38, v249, v38
	v_cndmask_b32_e64 v35, v41, v43, s[40:41]
	s_waitcnt lgkmcnt(2)
	v_add_f32_e32 v35, v35, v36
	v_cndmask_b32_e64 v36, v40, v48, s[40:41]
	s_waitcnt lgkmcnt(1)
	v_add_f32_e32 v36, v36, v37
	v_cndmask_b32_e64 v37, v39, v49, s[40:41]
	s_waitcnt lgkmcnt(0)
	v_add_f32_e32 v37, v37, v38
	v_cndmask_b32_e64 v38, v34, v42, s[40:41]
	v_cndmask_b32_e64 v34, v42, v34, s[40:41]
	ds_bpermute_b32 v34, v249, v34
	s_waitcnt lgkmcnt(0)
	v_add_f32_e32 v34, v38, v34
	v_cndmask_b32_e64 v38, v37, v35, s[42:43]
	v_cndmask_b32_e64 v35, v35, v37, s[42:43]
	v_cndmask_b32_e64 v37, v34, v36, s[42:43]
	v_cndmask_b32_e64 v34, v36, v34, s[42:43]
	ds_bpermute_b32 v35, v248, v35
	ds_bpermute_b32 v34, v248, v34
	s_waitcnt lgkmcnt(1)
	v_add_f32_e32 v35, v38, v35
	s_waitcnt lgkmcnt(0)
	v_add_f32_e32 v34, v37, v34
	v_cndmask_b32_e64 v36, v34, v35, s[44:45]
	v_cndmask_b32_e64 v34, v35, v34, s[44:45]
	ds_bpermute_b32 v34, v247, v34
	s_waitcnt lgkmcnt(0)
	v_add_f32_e32 v34, v36, v34
	ds_bpermute_b32 v35, v246, v34
	s_waitcnt lgkmcnt(0)
	v_add_f32_e32 v34, v34, v35
	ds_bpermute_b32 v35, v245, v34
	s_waitcnt lgkmcnt(0)
	v_add_f32_e32 v34, v34, v35
	ds_bpermute_b32 v35, v244, v34
	s_and_saveexec_b64 s[18:19], s[46:47]
	s_cbranch_execz .LBB0_450
	s_lshl_b64 s[2:3], s[52:53], 5
	s_waitcnt lgkmcnt(0)
	v_add_f32_e32 v36, v34, v35
	v_lshl_add_u64 v[34:35], v[64:65], 0, s[2:3]
	global_store_dword v[34:35], v36, off
	s_branch .LBB0_450
